# deferred hooks units 8,8,7,7 (more transposes hidden in idle GEMM rounds)
# speedup vs baseline: 1.0198x; 1.0006x over previous
; __device__ __forceinline__ int get_bid() { int b = blockIdx.x; asm volatile("" : "+s"(b)); return b; }
; __device__ __forceinline__ void deferred_work(const Params& P, LAS unsigned char* lds, int maxclaims, int units, int limit_items) {
;     ...
;     for (int n = 0; n < maxclaims; ++n) {
;         __syncthreads();
;         if (tid == 0) { int c = -1; const unsigned cur = __hip_atomic_load(ctr, __ATOMIC_RELAXED, __HIP_MEMORY_SCOPE_AGENT);
;             const int stop = limit_items > 0 ? limit_items : TR_DEF;
;             if ((int)cur * DCH < stop) c = (int)atomicAdd(ctr, (unsigned)units);
;             *sc = c; }
; __global__ void __launch_bounds__(NTHR, 2) mega_fwd(Params P) {
;     ...
;                 if (DEFER && DEFER_HOOKS && rep == 0 && ph == 6 && get_bid() >= (S.nwg % (int)gridDim.x)) deferred_work(P, lds, 1, 3, 0); } break;
.LBB0_886:
	v_readlane_b32 s0, v253, 26
	v_readlane_b32 s1, v253, 27
	s_andn2_b64 vcc, exec, s[0:1]
	s_cbranch_vccnz .LBB0_926
	s_abs_i32 s0, s34
	v_cvt_f32_u32_e32 v0, s0
	s_sub_i32 s2, 0, s0
	s_mov_b32 s1, s74
	v_rcp_iflag_f32_e32 v0, v0
	s_nop 0
	v_mul_f32_e32 v0, 0x4f7ffffe, v0
	v_cvt_u32_f32_e32 v0, v0
	s_nop 0
	v_readfirstlane_b32 s3, v0
	s_mul_i32 s2, s2, s3
	s_mul_hi_u32 s2, s3, s2
	s_add_i32 s3, s3, s2
	s_mul_hi_u32 s2, s30, s3
	s_mul_i32 s2, s2, s0
	s_sub_i32 s2, s30, s2
	s_sub_i32 s3, s2, s0
	s_cmp_ge_u32 s2, s0
	s_cselect_b32 s2, s3, s2
	s_sub_i32 s3, s2, s0
	s_cmp_ge_u32 s2, s0
	s_cselect_b32 s0, s3, s2
	s_cmp_lt_i32 s1, s0
	s_cbranch_scc1 .LBB0_926
	v_mov_b32_e32 v14, v196
	s_waitcnt vmcnt(0) lgkmcnt(0)
	v_cmp_eq_u32_e32 vcc, 0, v14
	s_barrier
	s_and_saveexec_b64 s[0:1], vcc
	s_cbranch_execz .LBB0_894
	global_load_dword v2, v1, s[72:73] sc1
	s_movk_i32 s2, 0x179f
	v_mov_b32_e32 v0, -1
	s_waitcnt vmcnt(0)
	v_cmp_lt_i32_e32 vcc, s2, v2
	s_cbranch_vccnz .LBB0_893
	s_mov_b64 s[6:7], exec
	v_mbcnt_lo_u32_b32 v0, s6, 0
	v_mbcnt_hi_u32_b32 v0, s7, v0
	v_cmp_eq_u32_e32 vcc, 0, v0
	s_and_saveexec_b64 s[4:5], vcc
	s_cbranch_execz .LBB0_892
	s_bcnt1_i32_b64 s2, s[6:7]
	s_mul_i32 s2, s2, 7
	v_mov_b32_e32 v2, s2
	global_atomic_add v2, v1, v2, s[72:73] sc0
.LBB0_892:
	s_or_b64 exec, exec, s[4:5]
	s_waitcnt vmcnt(0)
	v_readfirstlane_b32 s2, v2
	s_nop 1
	v_mad_u32_u24 v0, v0, 7, s2

; __device__ __forceinline__ TDesc tr_decode(const Params& P, unsigned char* ws, int it, int deferred) {
;     int r = it;
;     if (deferred) {
;         if (r < TR_WI) return tr_mk(P.ffn_wi + (size_t)1024 * 7168, 1024, 7168, (bf16_t*)(ws + O_FWI) + (size_t)7168 * 1024, 1, r); r -= TR_WI;
;         if (r < TR_WO) return tr_mk(P.ffn_wo + (size_t)3584 * 1024, 3584, 1024, (bf16_t*)(ws + O_FWO) + (size_t)1024 * 3584, 0, r); r -= TR_WO;
;         if (r < 8 * TR_WI) { const int e = 8 + r / TR_WI; return tr_mk(P.moe_wi + (size_t)e * 1024 * 7168, 1024, 7168, (bf16_t*)(ws + O_MWI) + (size_t)e * 7168 * 1024, 1, r % TR_WI); } r -= 8 * TR_WI;
;         { const int e = 8 + r / TR_WO; return tr_mk(P.moe_wo + (size_t)e * 3584 * 1024, 3584, 1024, (bf16_t*)(ws + O_MWO) + (size_t)e * 1024 * 3584, 0, r % TR_WO); }
; __device__ __forceinline__ void deferred_work(const Params& P, LAS unsigned char* lds, int maxclaims, int units, int limit_items) {
;     ...
;         const int c = *sc, base = c * DCH;
;         if (c < 0 || base >= TR_DEF) break;
;         const int cend = base + units * DCH, i1 = cend < TR_DEF ? cend : TR_DEF;
;         int it = base + wave;
;         float v[32]; TDesc cur;
;         if (it < i1) { cur = tr_decode(P, ws, it, 1); tr_load(cur, v, lane); }
;         while (it < i1) {
;             const int nit = it + NWAVE; float w[32]; TDesc nx = cur;
;             if (nit < i1) { nx = tr_decode(P, ws, nit, 1); tr_load(nx, w, lane); }
.LBB0_894:
	s_or_b64 exec, exec, s[0:1]
	v_lshlrev_b32_e32 v0, 3, v14
	v_and_b32_e32 v18, 56, v0
	v_mov_b32_e32 v0, s69
	s_waitcnt lgkmcnt(0)
	s_barrier
	ds_read_b32 v0, v0
	s_movk_i32 s0, 0x179f
	v_bfe_u32 v9, v14, 5, 1
	v_and_b32_e32 v8, 63, v14
	v_mul_u32_u24_e32 v15, 0x84, v9
	s_waitcnt lgkmcnt(0)
	v_cmp_lt_u32_e32 vcc, s0, v0
	v_mul_u32_u24_e32 v10, 0x84, v18
	s_cbranch_vccnz .LBB0_925
	v_lshlrev_b32_e32 v0, 3, v0
	v_ashrrev_i32_e32 v12, 6, v14
	v_min_u32_e32 v2, 0xbcc8, v0
	v_add_u32_e32 v11, 56, v2
	v_add_u32_e32 v16, v0, v12
	v_cmp_lt_i32_e32 vcc, v16, v11
	s_and_saveexec_b64 s[4:5], vcc
	s_cbranch_execz .LBB0_924
	s_movk_i32 s0, 0xdff
	v_cmp_lt_i32_e32 vcc, s0, v16
	s_and_saveexec_b64 s[0:1], vcc
	s_xor_b64 s[0:1], exec, s[0:1]
	s_cbranch_execz .LBB0_906
	v_cmp_lt_u32_e32 vcc, s62, v16
	s_and_saveexec_b64 s[6:7], vcc
	s_xor_b64 s[6:7], exec, s[6:7]
	s_cbranch_execz .LBB0_903
	s_mov_b32 s2, 0x84ff
	v_cmp_lt_u32_e32 vcc, s2, v16
	s_and_saveexec_b64 s[8:9], vcc
	s_xor_b64 s[8:9], exec, s[8:9]
	s_cbranch_execz .LBB0_900
	v_add_u16_e32 v0, 0x7b00, v16
	s_movk_i32 s2, 0x2493
	v_mul_u32_u24_sdwa v13, v0, s2 dst_sel:DWORD dst_unused:UNUSED_PAD src0_sel:BYTE_1 src1_sel:DWORD
	v_add_u16_sdwa v6, v13, v201 dst_sel:DWORD dst_unused:UNUSED_PAD src0_sel:WORD_1 src1_sel:DWORD
	v_mov_b64_e32 v[2:3], s[24:25]
	s_mov_b32 s2, 0xe00000
	v_mad_u64_u32 v[2:3], s[10:11], v6, s2, v[2:3]
	v_mov_b64_e32 v[4:5], s[52:53]
	s_mov_b32 s2, 0x700000
	v_mad_u64_u32 v[6:7], s[10:11], v6, s2, v[4:5]
	s_movk_i32 s2, 0x700
	v_mul_lo_u16_sdwa v4, v13, s2 dst_sel:DWORD dst_unused:UNUSED_PAD src0_sel:WORD_1 src1_sel:DWORD
	v_sub_u16_e32 v0, v0, v4
	v_lshlrev_b16_e32 v4, 5, v0
	v_lshlrev_b16_e32 v0, 1, v0
	v_and_b32_e32 v4, 0x3e0, v4
	v_and_b32_e32 v13, 0xfc0, v0
	v_lshlrev_b32_sdwa v0, v202, v13 dst_sel:DWORD dst_unused:UNUSED_PAD src0_sel:DWORD src1_sel:WORD_0
	v_and_b32_e32 v17, 0xffff, v4
	v_lshl_add_u64 v[2:3], v[2:3], 0, v[0:1]
	v_lshlrev_b32_e32 v0, 2, v17
	s_movk_i32 s2, 0x1c00
	v_lshl_add_u64 v[4:5], v[2:3], 0, v[0:1]
	v_mad_u64_u32 v[2:3], s[10:11], v17, s2, v[6:7]
	v_lshlrev_b32_sdwa v0, v200, v13 dst_sel:DWORD dst_unused:UNUSED_PAD src0_sel:DWORD src1_sel:WORD_0
	v_lshl_add_u64 v[2:3], v[2:3], 0, v[0:1]

; __device__ __forceinline__ int get_bid() { int b = blockIdx.x; asm volatile("" : "+s"(b)); return b; }
; __device__ __forceinline__ void deferred_work(const Params& P, LAS unsigned char* lds, int maxclaims, int units, int limit_items) {
;     ...
;     for (int n = 0; n < maxclaims; ++n) {
;         __syncthreads();
;         if (tid == 0) { int c = -1; const unsigned cur = __hip_atomic_load(ctr, __ATOMIC_RELAXED, __HIP_MEMORY_SCOPE_AGENT);
;             const int stop = limit_items > 0 ? limit_items : TR_DEF;
;             if ((int)cur * DCH < stop) c = (int)atomicAdd(ctr, (unsigned)units);
;             *sc = c; }
; __global__ void __launch_bounds__(NTHR, 2) mega_fwd(Params P) {
;     ...
;                 if (DEFER && DEFER_HOOKS && rep == 0 && ph == 2 && get_bid() >= (S.nwg % (int)gridDim.x)) deferred_work(P, lds, 1, 3, 0); } break;
.LBB0_1037:
	v_readlane_b32 s0, v253, 32
	v_readlane_b32 s1, v253, 33
	s_andn2_b64 vcc, exec, s[0:1]
	s_cbranch_vccnz .LBB0_1077
	s_abs_i32 s0, s21
	v_cvt_f32_u32_e32 v0, s0
	s_sub_i32 s2, 0, s0
	s_mov_b32 s1, s74
	v_rcp_iflag_f32_e32 v0, v0
	s_nop 0
	v_mul_f32_e32 v0, 0x4f7ffffe, v0
	v_cvt_u32_f32_e32 v0, v0
	s_nop 0
	v_readfirstlane_b32 s3, v0
	s_mul_i32 s2, s2, s3
	s_mul_hi_u32 s2, s3, s2
	s_add_i32 s3, s3, s2
	s_mul_hi_u32 s2, s20, s3
	s_mul_i32 s2, s2, s0
	s_sub_i32 s2, s20, s2
	s_sub_i32 s3, s2, s0
	s_cmp_ge_u32 s2, s0
	s_cselect_b32 s2, s3, s2
	s_sub_i32 s3, s2, s0
	s_cmp_ge_u32 s2, s0
	s_cselect_b32 s0, s3, s2
	s_cmp_lt_i32 s1, s0
	s_cbranch_scc1 .LBB0_1077
	v_mov_b32_e32 v14, v196
	s_waitcnt vmcnt(0) lgkmcnt(0)
	v_cmp_eq_u32_e32 vcc, 0, v14
	s_barrier
	s_and_saveexec_b64 s[0:1], vcc
	s_cbranch_execz .LBB0_1045
	global_load_dword v2, v1, s[72:73] sc1
	s_movk_i32 s2, 0x179f
	v_mov_b32_e32 v0, -1
	s_waitcnt vmcnt(0)
	v_cmp_lt_i32_e32 vcc, s2, v2
	s_cbranch_vccnz .LBB0_1044
	s_mov_b64 s[6:7], exec
	v_mbcnt_lo_u32_b32 v0, s6, 0
	v_mbcnt_hi_u32_b32 v0, s7, v0
	v_cmp_eq_u32_e32 vcc, 0, v0
	s_and_saveexec_b64 s[4:5], vcc
	s_cbranch_execz .LBB0_1043
	s_bcnt1_i32_b64 s2, s[6:7]
	s_mul_i32 s2, s2, 7
	v_mov_b32_e32 v2, s2
	global_atomic_add v2, v1, v2, s[72:73] sc0

; __device__ __forceinline__ TDesc tr_decode(const Params& P, unsigned char* ws, int it, int deferred) {
;     int r = it;
;     if (deferred) {
;         if (r < TR_WI) return tr_mk(P.ffn_wi + (size_t)1024 * 7168, 1024, 7168, (bf16_t*)(ws + O_FWI) + (size_t)7168 * 1024, 1, r); r -= TR_WI;
;         if (r < TR_WO) return tr_mk(P.ffn_wo + (size_t)3584 * 1024, 3584, 1024, (bf16_t*)(ws + O_FWO) + (size_t)1024 * 3584, 0, r); r -= TR_WO;
;         if (r < 8 * TR_WI) { const int e = 8 + r / TR_WI; return tr_mk(P.moe_wi + (size_t)e * 1024 * 7168, 1024, 7168, (bf16_t*)(ws + O_MWI) + (size_t)e * 7168 * 1024, 1, r % TR_WI); } r -= 8 * TR_WI;
;         { const int e = 8 + r / TR_WO; return tr_mk(P.moe_wo + (size_t)e * 3584 * 1024, 3584, 1024, (bf16_t*)(ws + O_MWO) + (size_t)e * 1024 * 3584, 0, r % TR_WO); }
; __device__ __forceinline__ void deferred_work(const Params& P, LAS unsigned char* lds, int maxclaims, int units, int limit_items) {
;     ...
;         const int c = *sc, base = c * DCH;
;         if (c < 0 || base >= TR_DEF) break;
;         const int cend = base + units * DCH, i1 = cend < TR_DEF ? cend : TR_DEF;
;         int it = base + wave;
;         float v[32]; TDesc cur;
;         if (it < i1) { cur = tr_decode(P, ws, it, 1); tr_load(cur, v, lane); }
;         while (it < i1) {
;             const int nit = it + NWAVE; float w[32]; TDesc nx = cur;
;             if (nit < i1) { nx = tr_decode(P, ws, nit, 1); tr_load(nx, w, lane); }
.LBB0_1045:
	s_or_b64 exec, exec, s[0:1]
	v_lshlrev_b32_e32 v0, 3, v14
	v_and_b32_e32 v18, 56, v0
	v_mov_b32_e32 v0, s69
	s_waitcnt lgkmcnt(0)
	s_barrier
	ds_read_b32 v0, v0
	s_movk_i32 s0, 0x179f
	v_bfe_u32 v9, v14, 5, 1
	v_and_b32_e32 v8, 63, v14
	v_mul_u32_u24_e32 v15, 0x84, v9
	s_waitcnt lgkmcnt(0)
	v_cmp_lt_u32_e32 vcc, s0, v0
	v_mul_u32_u24_e32 v10, 0x84, v18
	s_movk_i32 s20, 0xdf7
	s_cbranch_vccnz .LBB0_1076
	v_lshlrev_b32_e32 v0, 3, v0
	v_ashrrev_i32_e32 v12, 6, v14
	v_min_u32_e32 v2, 0xbcc8, v0
	v_add_u32_e32 v11, 56, v2
	v_add_u32_e32 v16, v0, v12
	v_cmp_lt_i32_e32 vcc, v16, v11
	s_and_saveexec_b64 s[4:5], vcc
	s_cbranch_execz .LBB0_1075
	s_movk_i32 s0, 0xdff
	v_cmp_lt_i32_e32 vcc, s0, v16
	s_and_saveexec_b64 s[0:1], vcc
	s_xor_b64 s[0:1], exec, s[0:1]
	s_cbranch_execz .LBB0_1057
	v_cmp_lt_u32_e32 vcc, s62, v16
	s_and_saveexec_b64 s[6:7], vcc
	s_xor_b64 s[6:7], exec, s[6:7]
	s_cbranch_execz .LBB0_1054
	s_mov_b32 s2, 0x84ff
	v_cmp_lt_u32_e32 vcc, s2, v16
	s_and_saveexec_b64 s[8:9], vcc
	s_xor_b64 s[8:9], exec, s[8:9]
	s_cbranch_execz .LBB0_1051
	v_add_u16_e32 v0, 0x7b00, v16
	s_movk_i32 s2, 0x2493
	v_mul_u32_u24_sdwa v13, v0, s2 dst_sel:DWORD dst_unused:UNUSED_PAD src0_sel:BYTE_1 src1_sel:DWORD
	v_add_u16_sdwa v6, v13, v201 dst_sel:DWORD dst_unused:UNUSED_PAD src0_sel:WORD_1 src1_sel:DWORD
	v_mov_b64_e32 v[2:3], s[24:25]
	s_mov_b32 s2, 0xe00000
	v_mad_u64_u32 v[2:3], s[10:11], v6, s2, v[2:3]
	v_mov_b64_e32 v[4:5], s[52:53]
	s_mov_b32 s2, 0x700000
	v_mad_u64_u32 v[6:7], s[10:11], v6, s2, v[4:5]
	s_movk_i32 s2, 0x700
	v_mul_lo_u16_sdwa v4, v13, s2 dst_sel:DWORD dst_unused:UNUSED_PAD src0_sel:WORD_1 src1_sel:DWORD
	v_sub_u16_e32 v0, v0, v4
	v_lshlrev_b16_e32 v4, 5, v0
	v_lshlrev_b16_e32 v0, 1, v0
	v_and_b32_e32 v4, 0x3e0, v4
	v_and_b32_e32 v13, 0xfc0, v0
	v_lshlrev_b32_sdwa v0, v202, v13 dst_sel:DWORD dst_unused:UNUSED_PAD src0_sel:DWORD src1_sel:WORD_0
	v_and_b32_e32 v17, 0xffff, v4
	v_lshl_add_u64 v[2:3], v[2:3], 0, v[0:1]
	v_lshlrev_b32_e32 v0, 2, v17
	s_movk_i32 s2, 0x1c00
	v_lshl_add_u64 v[4:5], v[2:3], 0, v[0:1]
	v_mad_u64_u32 v[2:3], s[10:11], v17, s2, v[6:7]
	v_lshlrev_b32_sdwa v0, v200, v13 dst_sel:DWORD dst_unused:UNUSED_PAD src0_sel:DWORD src1_sel:WORD_0
	v_lshl_add_u64 v[2:3], v[2:3], 0, v[0:1]
